# attention row max across lane halves via v_permlane32_swap (VALU) instead of ds_bpermute behind the V fragment reads; V reads waited before first PV MFMA
# baseline (speedup 1.0000x reference)
; #define LAS __attribute__((address_space(3)))
; __device__ __forceinline__ void attn_tile(const LAS unsigned char* Kb, const LAS unsigned char* Vb, const LAS f32x4* bp, const bf16x8 (&qr)[4], f32x16 (&o)[2], float& m, float& l, int r32, int hi) {
;     ...
;     for (int j = 0; j < 4; ++j) { const f32x4 t0 = bp[j * 64], t1 = bp[(4 + j) * 64];
;         p0[4 * j] = t0[0]; p0[4 * j + 1] = t0[1]; p0[4 * j + 2] = t0[2]; p0[4 * j + 3] = t0[3]; p1[4 * j] = t1[0]; p1[4 * j + 1] = t1[1]; p1[4 * j + 2] = t1[2]; p1[4 * j + 3] = t1[3]; }
; #pragma unroll
;     for (int d0 = 0; d0 < 4; ++d0) {
;         const bf16x8 a0 = *(const LAS bf16x8*)(Kb + r32 * 144 + d0 * 32 + hi * 16);
;         const bf16x8 a1 = *(const LAS bf16x8*)(Kb + (32 + r32) * 144 + d0 * 32 + hi * 16);
;         p0 = __builtin_amdgcn_mfma_f32_32x32x16_bf16(a0, qr[d0], p0, 0, 0, 0);
;         p1 = __builtin_amdgcn_mfma_f32_32x32x16_bf16(a1, qr[d0], p1, 0, 0, 0);
;     }
;     float mx = fmaxf(p0[0], p1[0]);
; #pragma unroll
;     for (int r = 1; r < 16; ++r) mx = fmaxf(mx, fmaxf(p0[r], p1[r]));
;     mx = fmaxf(mx, __shfl_xor(mx, 32)) * C2;
;     if (__any(mx > m + 8.0f)) {
;         const float mn = fmaxf(m, mx), scl = __builtin_amdgcn_exp2f(m - mn); m = mn; l *= scl;
; #pragma unroll
;         for (int r = 0; r < 16; ++r) { o[0][r] *= scl; o[1][r] *= scl; }
;     }
.LBB0_73:
	s_cmp_lt_i32 s28, s25
	s_cselect_b64 s[30:31], -1, 0
	s_cmp_gt_i32 s28, s23
	s_cselect_b64 s[34:35], -1, 0
	s_or_b64 s[30:31], s[30:31], s[34:35]
	s_and_b64 vcc, exec, s[30:31]
	s_cbranch_vccnz .LBB0_77
	s_add_i32 s29, s22, s26
	s_add_i32 s29, s29, 1
	s_min_i32 s29, s29, 3
	v_lshl_add_u32 v158, s29, 14, v103
	ds_read_b128 v[48:51], v158 offset:36864
	ds_read_b128 v[52:55], v158 offset:37888
	ds_read_b128 v[56:59], v158 offset:38912
	ds_read_b128 v[60:63], v158 offset:39936
	ds_read_b128 v[138:141], v116 offset:0
	ds_read_b128 v[142:145], v116 offset:4608
	ds_read_b128 v[32:35], v158 offset:40960
	ds_read_b128 v[36:39], v158 offset:41984
	ds_read_b128 v[40:43], v158 offset:43008
	ds_read_b128 v[44:47], v158 offset:44032
	ds_read_b128 v[146:149], v116 offset:32
	ds_read_b128 v[150:153], v116 offset:4640
	ds_read_b128 v[154:157], v116 offset:64
	ds_read_b128 v[118:121], v116 offset:4672
	ds_read_b128 v[122:125], v116 offset:96
	v_add_u32_e32 v133, v113, v112
	v_xor_b32_e32 v132, 32, v200
	s_waitcnt vmcnt(2) lgkmcnt(10)
	v_mfma_f32_32x32x16_bf16 v[48:63], v[138:141], v[64:67], v[48:63]
	ds_read_b128 v[126:129], v116 offset:4704
	s_waitcnt lgkmcnt(6)
	v_mfma_f32_32x32x16_bf16 v[32:47], v[142:145], v[64:67], v[32:47]
	v_lshlrev_b32_e32 v132, 2, v132
	s_waitcnt lgkmcnt(5)
	v_mfma_f32_32x32x16_bf16 v[48:63], v[146:149], v[68:71], v[48:63]
	s_waitcnt lgkmcnt(4)
	v_mfma_f32_32x32x16_bf16 v[32:47], v[150:153], v[68:71], v[32:47]
	s_waitcnt lgkmcnt(3)
	v_mfma_f32_32x32x16_bf16 v[48:63], v[154:157], v[72:75], v[48:63]
	s_waitcnt lgkmcnt(2)
	v_mfma_f32_32x32x16_bf16 v[32:47], v[118:121], v[72:75], v[32:47]
	s_waitcnt lgkmcnt(1)
	v_mfma_f32_32x32x16_bf16 v[48:63], v[122:125], v[80:83], v[48:63]
	s_waitcnt lgkmcnt(0)
	v_mfma_f32_32x32x16_bf16 v[32:47], v[126:129], v[80:83], v[32:47]
	ds_read_b128 v[138:141], v133 offset:18432
	ds_read_b128 v[142:145], v133 offset:18464
	ds_read_b128 v[146:149], v133 offset:18496
	ds_read_b128 v[150:153], v133 offset:18528
	ds_read_b128 v[154:157], v133 offset:23040
	ds_read_b128 v[118:121], v133 offset:23072
	ds_read_b128 v[122:125], v133 offset:23104
	ds_read_b128 v[126:129], v133 offset:23136
	v_add_f32_e32 v159, 0x41000000, v117
	s_nop 1
	v_max3_f32 v130, v48, v49, v50
	v_max3_f32 v130, v130, v51, v52
	v_max3_f32 v130, v130, v53, v54
	v_max3_f32 v131, v32, v33, v34
	v_max3_f32 v130, v130, v55, v56
	v_max3_f32 v131, v131, v35, v36
	v_max3_f32 v130, v130, v57, v58
	v_max3_f32 v131, v131, v37, v38
	v_max3_f32 v130, v130, v59, v60
	v_max3_f32 v131, v131, v39, v40
	v_max3_f32 v130, v130, v61, v62
	v_max3_f32 v131, v131, v41, v42
	v_max_f32_e32 v130, v130, v63
	v_max3_f32 v131, v131, v43, v44
	v_max3_f32 v131, v131, v45, v46
	v_max_f32_e32 v131, v131, v47
	v_max_f32_e32 v130, v130, v131
	v_mov_b32_e32 v131, v130
	s_nop 1
	v_permlane32_swap_b32_e32 v130, v131
	v_max_f32_e32 v130, v130, v131
	v_mul_f32_e32 v130, 0x3e38aa3b, v130
	v_cmp_gt_f32_e32 vcc, v130, v159
	s_cbranch_vccz .Latt_keep_a
	v_max_f32_e32 v131, v117, v130
	v_sub_f32_e32 v117, v117, v131
	v_exp_f32_e32 v130, v117
	v_mov_b32_e32 v117, v131
	v_mul_f32_e32 v101, v101, v130
	v_pk_mul_f32 v[0:1], v[0:1], v[130:131] op_sel_hi:[1,0]
	v_pk_mul_f32 v[2:3], v[2:3], v[130:131] op_sel_hi:[1,0]
	v_pk_mul_f32 v[4:5], v[4:5], v[130:131] op_sel_hi:[1,0]
	v_pk_mul_f32 v[6:7], v[6:7], v[130:131] op_sel_hi:[1,0]
	v_pk_mul_f32 v[8:9], v[8:9], v[130:131] op_sel_hi:[1,0]
	v_pk_mul_f32 v[10:11], v[10:11], v[130:131] op_sel_hi:[1,0]
	v_pk_mul_f32 v[12:13], v[12:13], v[130:131] op_sel_hi:[1,0]
	v_pk_mul_f32 v[14:15], v[14:15], v[130:131] op_sel_hi:[1,0]
	v_pk_mul_f32 v[16:17], v[16:17], v[130:131] op_sel_hi:[1,0]
	v_pk_mul_f32 v[18:19], v[18:19], v[130:131] op_sel_hi:[1,0]
	v_pk_mul_f32 v[20:21], v[20:21], v[130:131] op_sel_hi:[1,0]
	v_pk_mul_f32 v[22:23], v[22:23], v[130:131] op_sel_hi:[1,0]
	v_pk_mul_f32 v[24:25], v[24:25], v[130:131] op_sel_hi:[1,0]
	v_pk_mul_f32 v[26:27], v[26:27], v[130:131] op_sel_hi:[1,0]
	v_pk_mul_f32 v[28:29], v[28:29], v[130:131] op_sel_hi:[1,0]
	v_pk_mul_f32 v[30:31], v[30:31], v[130:131] op_sel_hi:[1,0]

; #define LAS __attribute__((address_space(3)))
; __device__ __forceinline__ void attn_tile(const LAS unsigned char* Kb, const LAS unsigned char* Vb, const LAS f32x4* bp, const bf16x8 (&qr)[4], f32x16 (&o)[2], float& m, float& l, int r32, int hi) {
;     ...
;     for (int j = 0; j < 4; ++j) { const f32x4 t0 = bp[j * 64], t1 = bp[(4 + j) * 64];
;         p0[4 * j] = t0[0]; p0[4 * j + 1] = t0[1]; p0[4 * j + 2] = t0[2]; p0[4 * j + 3] = t0[3]; p1[4 * j] = t1[0]; p1[4 * j + 1] = t1[1]; p1[4 * j + 2] = t1[2]; p1[4 * j + 3] = t1[3]; }
; #pragma unroll
;     for (int d0 = 0; d0 < 4; ++d0) {
;         const bf16x8 a0 = *(const LAS bf16x8*)(Kb + r32 * 144 + d0 * 32 + hi * 16);
;         const bf16x8 a1 = *(const LAS bf16x8*)(Kb + (32 + r32) * 144 + d0 * 32 + hi * 16);
;         p0 = __builtin_amdgcn_mfma_f32_32x32x16_bf16(a0, qr[d0], p0, 0, 0, 0);
;         p1 = __builtin_amdgcn_mfma_f32_32x32x16_bf16(a1, qr[d0], p1, 0, 0, 0);
;     }
;     float mx = fmaxf(p0[0], p1[0]);
; #pragma unroll
;     for (int r = 1; r < 16; ++r) mx = fmaxf(mx, fmaxf(p0[r], p1[r]));
;     mx = fmaxf(mx, __shfl_xor(mx, 32)) * C2;
;     if (__any(mx > m + 8.0f)) {
;         const float mn = fmaxf(m, mx), scl = __builtin_amdgcn_exp2f(m - mn); m = mn; l *= scl;
; #pragma unroll
;         for (int r = 0; r < 16; ++r) { o[0][r] *= scl; o[1][r] *= scl; }
;     }
.LBB0_79:
	s_add_i32 s29, s28, 1
	s_cmp_lt_i32 s29, s25
	s_cselect_b64 s[30:31], -1, 0
	s_cmp_ge_i32 s28, s23
	s_cselect_b64 s[28:29], -1, 0
	s_or_b64 s[28:29], s[28:29], s[30:31]
	s_and_b64 vcc, exec, s[28:29]
	s_cbranch_vccnz .LBB0_83
	s_add_i32 s28, s22, s26
	s_min_i32 s28, s28, 3
	v_lshl_add_u32 v158, s28, 14, v103
	ds_read_b128 v[48:51], v158 offset:36864
	ds_read_b128 v[52:55], v158 offset:37888
	ds_read_b128 v[56:59], v158 offset:38912
	ds_read_b128 v[60:63], v158 offset:39936
	ds_read_b128 v[138:141], v116 offset:9216
	ds_read_b128 v[142:145], v116 offset:13824
	ds_read_b128 v[32:35], v158 offset:40960
	ds_read_b128 v[36:39], v158 offset:41984
	ds_read_b128 v[40:43], v158 offset:43008
	ds_read_b128 v[44:47], v158 offset:44032
	ds_read_b128 v[146:149], v116 offset:9248
	ds_read_b128 v[150:153], v116 offset:13856
	ds_read_b128 v[154:157], v116 offset:9280
	ds_read_b128 v[118:121], v116 offset:13888
	ds_read_b128 v[122:125], v116 offset:9312
	v_add_u32_e32 v133, v113, v112
	v_xor_b32_e32 v132, 32, v200
	s_waitcnt lgkmcnt(10)
	v_mfma_f32_32x32x16_bf16 v[48:63], v[138:141], v[64:67], v[48:63]
	ds_read_b128 v[126:129], v116 offset:13920
	s_waitcnt lgkmcnt(6)
	v_mfma_f32_32x32x16_bf16 v[32:47], v[142:145], v[64:67], v[32:47]
	v_lshlrev_b32_e32 v132, 2, v132
	s_waitcnt lgkmcnt(5)
	v_mfma_f32_32x32x16_bf16 v[48:63], v[146:149], v[68:71], v[48:63]
	s_waitcnt lgkmcnt(4)
	v_mfma_f32_32x32x16_bf16 v[32:47], v[150:153], v[68:71], v[32:47]
	s_waitcnt lgkmcnt(3)
	v_mfma_f32_32x32x16_bf16 v[48:63], v[154:157], v[72:75], v[48:63]
	s_waitcnt lgkmcnt(2)
	v_mfma_f32_32x32x16_bf16 v[32:47], v[118:121], v[72:75], v[32:47]
	s_waitcnt lgkmcnt(1)
	v_mfma_f32_32x32x16_bf16 v[48:63], v[122:125], v[80:83], v[48:63]
	s_waitcnt lgkmcnt(0)
	v_mfma_f32_32x32x16_bf16 v[32:47], v[126:129], v[80:83], v[32:47]
	ds_read_b128 v[138:141], v133 offset:27648
	ds_read_b128 v[142:145], v133 offset:27680
	ds_read_b128 v[146:149], v133 offset:27712
	ds_read_b128 v[150:153], v133 offset:27744
	ds_read_b128 v[154:157], v133 offset:32256
	ds_read_b128 v[118:121], v133 offset:32288
	ds_read_b128 v[122:125], v133 offset:32320
	ds_read_b128 v[126:129], v133 offset:32352
	v_add_f32_e32 v159, 0x41000000, v117
	s_nop 1
	v_max3_f32 v130, v48, v49, v50
	v_max3_f32 v130, v130, v51, v52
	v_max3_f32 v130, v130, v53, v54
	v_max3_f32 v131, v32, v33, v34
	v_max3_f32 v130, v130, v55, v56
	v_max3_f32 v131, v131, v35, v36
	v_max3_f32 v130, v130, v57, v58
	v_max3_f32 v131, v131, v37, v38
	v_max3_f32 v130, v130, v59, v60
	v_max3_f32 v131, v131, v39, v40
	v_max3_f32 v130, v130, v61, v62
	v_max3_f32 v131, v131, v41, v42
	v_max_f32_e32 v130, v130, v63
	v_max3_f32 v131, v131, v43, v44
	v_max3_f32 v131, v131, v45, v46
	v_max_f32_e32 v131, v131, v47
	v_max_f32_e32 v130, v130, v131
	v_mov_b32_e32 v131, v130
	s_nop 1
	v_permlane32_swap_b32_e32 v130, v131
	v_max_f32_e32 v130, v130, v131
	v_mul_f32_e32 v130, 0x3e38aa3b, v130
	v_cmp_gt_f32_e32 vcc, v130, v159
	s_cbranch_vccz .Latt_keep_b
	v_max_f32_e32 v131, v117, v130
	v_sub_f32_e32 v117, v117, v131
	v_exp_f32_e32 v130, v117
	v_mov_b32_e32 v117, v131
	v_mul_f32_e32 v101, v101, v130
	v_pk_mul_f32 v[0:1], v[0:1], v[130:131] op_sel_hi:[1,0]
	v_pk_mul_f32 v[2:3], v[2:3], v[130:131] op_sel_hi:[1,0]
	v_pk_mul_f32 v[4:5], v[4:5], v[130:131] op_sel_hi:[1,0]
	v_pk_mul_f32 v[6:7], v[6:7], v[130:131] op_sel_hi:[1,0]
	v_pk_mul_f32 v[8:9], v[8:9], v[130:131] op_sel_hi:[1,0]
	v_pk_mul_f32 v[10:11], v[10:11], v[130:131] op_sel_hi:[1,0]
	v_pk_mul_f32 v[12:13], v[12:13], v[130:131] op_sel_hi:[1,0]
	v_pk_mul_f32 v[14:15], v[14:15], v[130:131] op_sel_hi:[1,0]
	v_pk_mul_f32 v[16:17], v[16:17], v[130:131] op_sel_hi:[1,0]
	v_pk_mul_f32 v[18:19], v[18:19], v[130:131] op_sel_hi:[1,0]
	v_pk_mul_f32 v[20:21], v[20:21], v[130:131] op_sel_hi:[1,0]
	v_pk_mul_f32 v[22:23], v[22:23], v[130:131] op_sel_hi:[1,0]
	v_pk_mul_f32 v[24:25], v[24:25], v[130:131] op_sel_hi:[1,0]
	v_pk_mul_f32 v[26:27], v[26:27], v[130:131] op_sel_hi:[1,0]
	v_pk_mul_f32 v[28:29], v[28:29], v[130:131] op_sel_hi:[1,0]
	v_pk_mul_f32 v[30:31], v[30:31], v[130:131] op_sel_hi:[1,0]
